# A/E K-loop: strict vmcnt wait on the fall-through path, relaxed wait out of line (no taken branch in steady state)
# baseline (speedup 1.0000x reference)
.LBB0_412:
	s_add_u32 s78, s8, 0x100
	s_addc_u32 s1, s9, 0
	s_ashr_i32 s53, s52, 31
	s_lshl_b64 s[4:5], s[52:53], 19
	s_add_u32 s58, s14, s4
	s_addc_u32 s59, s15, s5
	s_and_b64 s[4:5], s[2:3], exec
	s_cselect_b32 s4, s59, s55
	s_cselect_b32 s5, s58, s54
	s_ashr_i32 s83, s82, 31
	s_lshl_b64 s[10:11], s[82:83], 19
	v_readlane_b32 s12, v251, 26
	s_add_u32 s26, s12, s10
	v_readlane_b32 s10, v250, 6
	s_addc_u32 s27, s10, s11
	s_and_b64 s[10:11], s[2:3], exec
	s_cselect_b32 s12, s27, s9
	s_cselect_b32 s13, s26, s8
	s_add_u32 s8, s54, 0x40080
	s_addc_u32 s9, s55, 0
	v_lshl_add_u64 v[132:133], s[8:9], 0, v[190:191]
	v_lshl_add_u64 v[134:135], s[8:9], 0, v[192:193]
	s_mov_b32 s17, -2
	s_mov_b64 s[8:9], 0
	s_branch .Lvr_a_entry
.Lvr_a1_relax:
	s_waitcnt vmcnt(24)
	s_sub_u32 s100, s100, 1
	s_branch .Lvr_a1_done
.Lvr_a2_relax:
	s_waitcnt vmcnt(24)
	s_sub_u32 s100, s100, 1
	s_branch .Lvr_a2_done
	.p2align	6
.Lvr_a_entry:
.LBB0_413:
	s_add_u32 s10, s54, s8
	s_addc_u32 s11, s55, s9
	s_add_u32 s10, s10, 0x100
	s_addc_u32 s11, s11, 0
	s_add_u32 s18, s78, s8
	s_addc_u32 s24, s1, s9
	s_add_i32 s25, 0, 0x10000
	s_cmpk_eq_i32 s8, 0x700
	s_cselect_b32 s15, s4, s11
	s_cselect_b32 s14, s5, s10
	v_add_u32_e32 v14, s25, v206
	s_cselect_b32 s11, s12, s24
	s_cselect_b32 s10, s13, s18
	s_add_i32 s18, 0, 0x14000
	ds_read_b128 v[136:139], v14
	ds_read_b128 v[140:143], v14 offset:1024
	ds_read_b128 v[144:147], v14 offset:2048
	ds_read_b128 v[148:151], v14 offset:3072
	v_add_u32_e32 v14, s18, v206
	ds_read_b128 v[152:155], v14
	ds_read_b128 v[156:159], v14 offset:1024
	ds_read_b128 v[160:163], v14 offset:2048
	ds_read_b128 v[164:167], v14 offset:3072
	v_lshl_add_u64 v[224:225], v[132:133], 0, s[8:9]
	s_add_i32 m0, s51, 0xc000
	ds_read_b128 v[168:171], v213
	ds_read_b128 v[172:175], v213 offset:1024
	ds_read_b128 v[176:179], v213 offset:2048
	ds_read_b128 v[194:197], v213 offset:3072
	ds_read_b128 v[198:201], v213 offset:4096
	ds_read_b128 v[202:205], v213 offset:5120
	ds_read_b128 v[216:219], v213 offset:6144
	ds_read_b128 v[220:223], v213 offset:7168
	global_load_lds_dwordx4 v[224:225], off
	v_lshl_add_u64 v[224:225], v[134:135], 0, s[8:9]
	s_add_i32 m0, s51, 0xe000
	s_nop 0
	global_load_lds_dwordx4 v[224:225], off
	s_cmp_lg_u32 s100, 0
	s_cbranch_scc1 .Lvr_a1_relax
	s_waitcnt vmcnt(8)
.Lvr_a1_done:
	s_waitcnt lgkmcnt(0)
	s_barrier
	s_setprio 1
	s_waitcnt lgkmcnt(0)
	v_mfma_f32_16x16x32_bf16 v[128:131], v[136:139], v[168:171], v[128:131]
	v_mfma_f32_16x16x32_bf16 v[124:127], v[144:147], v[168:171], v[124:127]
	v_mfma_f32_16x16x32_bf16 v[120:123], v[136:139], v[176:179], v[120:123]
	v_mfma_f32_16x16x32_bf16 v[116:119], v[144:147], v[176:179], v[116:119]
	v_mfma_f32_16x16x32_bf16 v[112:115], v[136:139], v[198:201], v[112:115]
	v_mfma_f32_16x16x32_bf16 v[108:111], v[144:147], v[198:201], v[108:111]
	v_mfma_f32_16x16x32_bf16 v[104:107], v[136:139], v[216:219], v[104:107]
	v_mfma_f32_16x16x32_bf16 v[100:103], v[144:147], v[216:219], v[100:103]
	v_mfma_f32_16x16x32_bf16 v[128:131], v[140:143], v[172:175], v[128:131]
	v_mfma_f32_16x16x32_bf16 v[124:127], v[148:151], v[172:175], v[124:127]
	v_mfma_f32_16x16x32_bf16 v[120:123], v[140:143], v[194:197], v[120:123]
	v_mfma_f32_16x16x32_bf16 v[116:119], v[148:151], v[194:197], v[116:119]
	v_mfma_f32_16x16x32_bf16 v[112:115], v[140:143], v[202:205], v[112:115]
	v_mfma_f32_16x16x32_bf16 v[108:111], v[148:151], v[202:205], v[108:111]
	v_mfma_f32_16x16x32_bf16 v[104:107], v[140:143], v[220:223], v[104:107]
	v_mfma_f32_16x16x32_bf16 v[100:103], v[148:151], v[220:223], v[100:103]
	s_setprio 0
	s_setprio 1
	v_mfma_f32_16x16x32_bf16 v[96:99], v[152:155], v[168:171], v[96:99]
	v_mfma_f32_16x16x32_bf16 v[92:95], v[160:163], v[168:171], v[92:95]
	v_mfma_f32_16x16x32_bf16 v[88:91], v[152:155], v[176:179], v[88:91]
	v_mfma_f32_16x16x32_bf16 v[84:87], v[160:163], v[176:179], v[84:87]
	v_mfma_f32_16x16x32_bf16 v[80:83], v[152:155], v[198:201], v[80:83]
	v_mfma_f32_16x16x32_bf16 v[76:79], v[160:163], v[198:201], v[76:79]
	v_mfma_f32_16x16x32_bf16 v[72:75], v[152:155], v[216:219], v[72:75]
	v_mfma_f32_16x16x32_bf16 v[68:71], v[160:163], v[216:219], v[68:71]
	v_mfma_f32_16x16x32_bf16 v[96:99], v[156:159], v[172:175], v[96:99]
	v_mfma_f32_16x16x32_bf16 v[92:95], v[164:167], v[172:175], v[92:95]
	v_mfma_f32_16x16x32_bf16 v[88:91], v[156:159], v[194:197], v[88:91]
	v_mfma_f32_16x16x32_bf16 v[84:87], v[164:167], v[194:197], v[84:87]
	v_mfma_f32_16x16x32_bf16 v[80:83], v[156:159], v[202:205], v[80:83]
	v_mfma_f32_16x16x32_bf16 v[76:79], v[164:167], v[202:205], v[76:79]
	v_mfma_f32_16x16x32_bf16 v[72:75], v[156:159], v[220:223], v[72:75]
	v_mfma_f32_16x16x32_bf16 v[68:71], v[164:167], v[220:223], v[68:71]
	s_setprio 0
	s_barrier
	s_add_i32 s24, s25, s81
	v_lshl_add_u64 v[224:225], s[10:11], 0, v[182:183]
	s_mov_b32 m0, s24
	ds_read_b128 v[168:171], v213 offset:16384
	ds_read_b128 v[172:175], v213 offset:17408
	ds_read_b128 v[176:179], v213 offset:18432
	ds_read_b128 v[194:197], v213 offset:19456
	ds_read_b128 v[198:201], v213 offset:20480
	ds_read_b128 v[202:205], v213 offset:21504
	ds_read_b128 v[216:219], v213 offset:22528
	ds_read_b128 v[220:223], v213 offset:23552
	global_load_lds_dwordx4 v[224:225], off
	s_add_i32 m0, s24, 0x2000
	s_add_u32 s24, s10, 0x40000
	v_lshl_add_u64 v[232:233], s[10:11], 0, v[186:187]
	s_addc_u32 s25, s11, 0
	s_add_i32 s18, s18, s81
	global_load_lds_dwordx4 v[232:233], off
	v_lshl_add_u64 v[234:235], s[24:25], 0, v[182:183]
	s_mov_b32 m0, s18
	v_lshl_add_u64 v[238:239], s[14:15], 0, v[184:185]
	global_load_lds_dwordx4 v[234:235], off
	v_lshl_add_u64 v[234:235], s[24:25], 0, v[186:187]
	s_add_i32 m0, s18, 0x2000
	s_nop 0
	global_load_lds_dwordx4 v[234:235], off
	v_lshl_add_u64 v[234:235], s[14:15], 0, v[180:181]
	s_mov_b32 m0, s51
	s_nop 0
	global_load_lds_dwordx4 v[234:235], off
	s_mov_b32 m0, s57
	s_nop 0
	global_load_lds_dwordx4 v[238:239], off
	s_cmp_lg_u32 s100, 0
	s_cbranch_scc1 .Lvr_a2_relax
	s_waitcnt vmcnt(8)

.LBB0_1773:
	s_ashr_i32 s83, s82, 31
	s_lshl_b64 s[2:3], s[82:83], 19
	s_add_u32 s58, s10, s2
	s_addc_u32 s59, s11, s3
	s_and_b64 s[2:3], s[52:53], exec
	s_cselect_b32 s4, s59, s49
	s_cselect_b32 s5, s58, s48
	s_ashr_i32 s9, s8, 31
	s_lshl_b64 s[2:3], s[8:9], 19
	s_add_u32 s2, s61, s2
	v_readlane_b32 s9, v250, 10
	s_addc_u32 s3, s9, s3
	s_and_b64 s[10:11], s[52:53], exec
	s_cselect_b32 s9, s3, s21
	s_cselect_b32 s12, s2, s20
	s_mov_b32 s13, -2
	s_mov_b64 s[38:39], 0
	s_branch .Lvr_e_entry
.Lvr_e1_relax:
	s_waitcnt vmcnt(16)
	s_sub_u32 s100, s100, 1
	s_branch .Lvr_e1_done
.Lvr_e2_relax:
	s_waitcnt vmcnt(16)
	s_sub_u32 s100, s100, 1
	s_branch .Lvr_e2_done
	.p2align	6
.Lvr_e_entry:
.LBB0_1774:
	s_add_u32 s17, s48, s38
	s_addc_u32 s29, s49, s39
	s_add_u32 s10, s17, 0x100
	v_add_u32_e32 v14, 0x10000, v249
	s_addc_u32 s11, s29, 0
	ds_read_b128 v[134:137], v14
	ds_read_b128 v[138:141], v14 offset:1024
	ds_read_b128 v[142:145], v14 offset:2048
	ds_read_b128 v[146:149], v14 offset:3072
	v_add_u32_e32 v14, 0x14000, v249
	s_add_u32 s14, s20, s38
	ds_read_b128 v[150:153], v14
	ds_read_b128 v[154:157], v14 offset:1024
	ds_read_b128 v[158:161], v14 offset:2048
	ds_read_b128 v[162:165], v14 offset:3072
	s_addc_u32 s15, s21, s39
	s_add_u32 s14, s14, 0x100
	s_addc_u32 s15, s15, 0
	s_cmp_eq_u32 s13, 12
	s_cselect_b32 s40, s5, s10
	s_cselect_b32 s41, s4, s11
	s_cselect_b32 s14, s12, s14
	s_cselect_b32 s15, s9, s15
	s_add_u32 s10, s40, 0x80
	s_addc_u32 s11, s41, 0
	ds_read_b128 v[166:169], v234
	ds_read_b128 v[170:173], v234 offset:1024
	ds_read_b128 v[174:177], v234 offset:2048
	ds_read_b128 v[178:181], v234 offset:3072
	ds_read_b128 v[182:185], v234 offset:4096
	ds_read_b128 v[186:189], v234 offset:5120
	ds_read_b128 v[190:193], v234 offset:6144
	ds_read_b128 v[194:197], v234 offset:7168
	s_add_u32 s28, s17, 0x40080
	s_addc_u32 s29, s29, 0
	s_mov_b32 m0, s80
	s_nop 0
	global_load_lds_dwordx4 v1, s[28:29]
	s_nop 0
	s_mov_b32 m0, s81
	s_nop 0
	global_load_lds_dwordx4 v239, s[28:29]
	s_cmp_lg_u32 s100, 0
	s_cbranch_scc1 .Lvr_e1_relax
	s_waitcnt vmcnt(8)
.Lvr_e1_done:
	s_waitcnt lgkmcnt(0)
	s_barrier
	s_setprio 1
	s_waitcnt lgkmcnt(7)
	v_mfma_f32_16x16x32_bf16 v[130:133], v[134:137], v[166:169], v[130:133]
	v_mfma_f32_16x16x32_bf16 v[126:129], v[142:145], v[166:169], v[126:129]
	s_waitcnt lgkmcnt(5)
	v_mfma_f32_16x16x32_bf16 v[122:125], v[134:137], v[174:177], v[122:125]
	v_mfma_f32_16x16x32_bf16 v[118:121], v[142:145], v[174:177], v[118:121]
	s_waitcnt lgkmcnt(3)
	v_mfma_f32_16x16x32_bf16 v[114:117], v[134:137], v[182:185], v[114:117]
	v_mfma_f32_16x16x32_bf16 v[110:113], v[142:145], v[182:185], v[110:113]
	s_waitcnt lgkmcnt(1)
	v_mfma_f32_16x16x32_bf16 v[106:109], v[134:137], v[190:193], v[106:109]
	v_mfma_f32_16x16x32_bf16 v[102:105], v[142:145], v[190:193], v[102:105]
	v_mfma_f32_16x16x32_bf16 v[130:133], v[138:141], v[170:173], v[130:133]
	v_mfma_f32_16x16x32_bf16 v[126:129], v[146:149], v[170:173], v[126:129]
	v_mfma_f32_16x16x32_bf16 v[122:125], v[138:141], v[178:181], v[122:125]
	v_mfma_f32_16x16x32_bf16 v[118:121], v[146:149], v[178:181], v[118:121]
	v_mfma_f32_16x16x32_bf16 v[114:117], v[138:141], v[186:189], v[114:117]
	v_mfma_f32_16x16x32_bf16 v[110:113], v[146:149], v[186:189], v[110:113]
	s_waitcnt lgkmcnt(0)
	v_mfma_f32_16x16x32_bf16 v[106:109], v[138:141], v[194:197], v[106:109]
	v_mfma_f32_16x16x32_bf16 v[102:105], v[146:149], v[194:197], v[102:105]
	s_setprio 0
	s_setprio 1
	v_mfma_f32_16x16x32_bf16 v[98:101], v[150:153], v[166:169], v[98:101]
	v_mfma_f32_16x16x32_bf16 v[94:97], v[158:161], v[166:169], v[94:97]
	v_mfma_f32_16x16x32_bf16 v[90:93], v[150:153], v[174:177], v[90:93]
	v_mfma_f32_16x16x32_bf16 v[86:89], v[158:161], v[174:177], v[86:89]
	v_mfma_f32_16x16x32_bf16 v[82:85], v[150:153], v[182:185], v[82:85]
	v_mfma_f32_16x16x32_bf16 v[78:81], v[158:161], v[182:185], v[78:81]
	v_mfma_f32_16x16x32_bf16 v[74:77], v[150:153], v[190:193], v[74:77]
	v_mfma_f32_16x16x32_bf16 v[70:73], v[158:161], v[190:193], v[70:73]
	v_mfma_f32_16x16x32_bf16 v[98:101], v[154:157], v[170:173], v[98:101]
	v_mfma_f32_16x16x32_bf16 v[94:97], v[162:165], v[170:173], v[94:97]
	v_mfma_f32_16x16x32_bf16 v[90:93], v[154:157], v[178:181], v[90:93]
	v_mfma_f32_16x16x32_bf16 v[86:89], v[162:165], v[178:181], v[86:89]
	v_mfma_f32_16x16x32_bf16 v[82:85], v[154:157], v[186:189], v[82:85]
	v_mfma_f32_16x16x32_bf16 v[78:81], v[162:165], v[186:189], v[78:81]
	v_mfma_f32_16x16x32_bf16 v[74:77], v[154:157], v[194:197], v[74:77]
	v_mfma_f32_16x16x32_bf16 v[70:73], v[162:165], v[194:197], v[70:73]
	s_setprio 0
	s_barrier
	ds_read_b128 v[166:169], v234 offset:16384
	ds_read_b128 v[170:173], v234 offset:17408
	ds_read_b128 v[174:177], v234 offset:18432
	ds_read_b128 v[178:181], v234 offset:19456
	ds_read_b128 v[182:185], v234 offset:20480
	ds_read_b128 v[186:189], v234 offset:21504
	ds_read_b128 v[190:193], v234 offset:22528
	ds_read_b128 v[194:197], v234 offset:23552
	s_mov_b32 m0, s47
	s_nop 0
	global_load_lds_dwordx4 v238, s[14:15]
	s_add_u32 s28, s14, 0x40000
	s_mov_b32 m0, s79
	s_nop 0
	global_load_lds_dwordx4 v240, s[14:15]
	s_addc_u32 s29, s15, 0
	s_mov_b32 m0, s78
	s_nop 0
	global_load_lds_dwordx4 v238, s[28:29]
	s_nop 0
	s_mov_b32 m0, s56
	s_nop 0
	global_load_lds_dwordx4 v240, s[28:29]
	s_nop 0
	s_mov_b32 m0, s45
	s_nop 0
	global_load_lds_dwordx4 v1, s[40:41]
	s_nop 0
	s_mov_b32 m0, s57
	s_nop 0
	global_load_lds_dwordx4 v239, s[40:41]
	s_cmp_lg_u32 s100, 0
	s_cbranch_scc1 .Lvr_e2_relax
	s_waitcnt vmcnt(8)
